# weight-conversion stores carry nt (streamed bf16 weight blocks); on top of peeled C=0 first K-iteration + no canonicalizing v_max + MFMA-head trim + barrier XGEN-first
# speedup vs baseline: 1.0084x; 1.0026x over previous
.LBB0_187:
	v_lshlrev_b32_e32 v134, 6, v134
	v_add_lshl_u32 v134, v134, s2, 1
	s_waitcnt lgkmcnt(0)
	v_cvt_pk_bf16_f32 v210, v138, v139
	v_lshl_add_u64 v[138:139], s[30:31], 0, v[134:135]
	v_mov_b32_e32 v137, v135
	v_cvt_pk_bf16_f32 v211, v140, v141
	v_cvt_pk_bf16_f32 v212, v142, v143
	v_cvt_pk_bf16_f32 v213, v144, v145
	v_lshl_add_u64 v[214:215], v[138:139], 0, v[136:137]
	ds_read2_b32 v[138:139], v162 offset0:8 offset1:73
	ds_read2_b32 v[140:141], v162 offset0:138 offset1:203
	ds_read2_b32 v[142:143], v177 offset0:12 offset1:77
	ds_read2_b32 v[144:145], v177 offset0:142 offset1:207
	v_cndmask_b32_e64 v134, 0, 1, s[8:9]
	v_cmp_ne_u32_e64 s[6:7], 1, v134
	s_andn2_b64 vcc, exec, s[8:9]
	global_store_dwordx4 v[214:215], v[210:213], off nt
	s_cbranch_vccnz .LBB0_219
	s_lshr_b32 s2, s52, 1
	v_or_b32_e32 v134, s2, v160
	s_mov_b32 s2, 0
	v_bitop3_b32 v209, s52, v170, v160 bitop3:0xc8
	s_cbranch_execnz .LBB0_190

.LBB0_190:
	s_waitcnt lgkmcnt(3)
	v_cvt_pk_bf16_f32 v210, v138, v139
	s_waitcnt lgkmcnt(2)
	v_cvt_pk_bf16_f32 v211, v140, v141
	s_waitcnt lgkmcnt(1)
	v_cvt_pk_bf16_f32 v212, v142, v143
	s_waitcnt lgkmcnt(0)
	v_cvt_pk_bf16_f32 v213, v144, v145
	ds_read2_b32 v[138:139], v162 offset0:16 offset1:81
	ds_read2_b32 v[140:141], v162 offset0:146 offset1:211
	ds_read2_b32 v[142:143], v177 offset0:20 offset1:85
	ds_read2_b32 v[144:145], v177 offset0:150 offset1:215
	v_add_u32_e32 v134, v134, v167
	v_lshl_or_b32 v134, v134, 6, v171
	v_add_lshl_u32 v134, v134, s2, 1
	v_lshl_add_u64 v[214:215], s[30:31], 0, v[134:135]
	v_mov_b32_e32 v137, v135
	v_lshl_add_u64 v[214:215], v[214:215], 0, v[136:137]
	s_and_b64 vcc, exec, s[6:7]
	global_store_dwordx4 v[214:215], v[210:213], off nt
	s_cbranch_vccnz .LBB0_220
	s_lshr_b32 s2, s52, 1
	v_or_b32_e32 v134, s2, v168
	s_mov_b32 s2, 0
	s_cbranch_execnz .LBB0_193

.LBB0_193:
	s_waitcnt lgkmcnt(3)
	v_cvt_pk_bf16_f32 v210, v138, v139
	s_waitcnt lgkmcnt(2)
	v_cvt_pk_bf16_f32 v211, v140, v141
	s_waitcnt lgkmcnt(1)
	v_cvt_pk_bf16_f32 v212, v142, v143
	s_waitcnt lgkmcnt(0)
	v_cvt_pk_bf16_f32 v213, v144, v145
	ds_read2_b32 v[138:139], v162 offset0:24 offset1:89
	ds_read2_b32 v[140:141], v162 offset0:154 offset1:219
	ds_read2_b32 v[142:143], v177 offset0:28 offset1:93
	ds_read2_b32 v[144:145], v177 offset0:158 offset1:223
	v_lshl_or_b32 v134, v134, 6, v172
	v_add_lshl_u32 v134, v134, s2, 1
	v_lshl_add_u64 v[214:215], s[30:31], 0, v[134:135]
	v_mov_b32_e32 v137, v135
	v_lshl_add_u64 v[214:215], v[214:215], 0, v[136:137]
	s_and_b64 vcc, exec, s[6:7]
	global_store_dwordx4 v[214:215], v[210:213], off nt
	s_cbranch_vccnz .LBB0_221
	s_lshr_b32 s2, s52, 1
	v_or_b32_e32 v134, s2, v160
	s_mov_b32 s2, 0
	s_cbranch_execnz .LBB0_196

.LBB0_196:
	s_waitcnt lgkmcnt(3)
	v_cvt_pk_bf16_f32 v208, v138, v139
	s_waitcnt lgkmcnt(2)
	v_cvt_pk_bf16_f32 v209, v140, v141
	s_waitcnt lgkmcnt(1)
	v_cvt_pk_bf16_f32 v210, v142, v143
	s_waitcnt lgkmcnt(0)
	v_cvt_pk_bf16_f32 v211, v144, v145
	ds_read2_b32 v[138:139], v162 offset0:32 offset1:97
	ds_read2_b32 v[140:141], v162 offset0:162 offset1:227
	ds_read2_b32 v[142:143], v177 offset0:36 offset1:101
	ds_read2_b32 v[144:145], v177 offset0:166 offset1:231
	v_or_b32_e32 v134, v134, v161
	v_lshl_or_b32 v134, v134, 6, v173
	v_add_lshl_u32 v134, v134, s2, 1
	v_lshl_add_u64 v[212:213], s[30:31], 0, v[134:135]
	v_mov_b32_e32 v137, v135
	v_lshl_add_u64 v[212:213], v[212:213], 0, v[136:137]
	s_and_b64 vcc, exec, s[6:7]
	global_store_dwordx4 v[212:213], v[208:211], off nt
	s_cbranch_vccnz .LBB0_222
	s_lshr_b32 s2, s52, 1
	v_or_b32_e32 v134, s2, v168
	s_movk_i32 s2, 0x2000
	s_cbranch_execnz .LBB0_199

.LBB0_199:
	s_waitcnt lgkmcnt(3)
	v_cvt_pk_bf16_f32 v208, v138, v139
	s_waitcnt lgkmcnt(2)
	v_cvt_pk_bf16_f32 v209, v140, v141
	s_waitcnt lgkmcnt(1)
	v_cvt_pk_bf16_f32 v210, v142, v143
	s_waitcnt lgkmcnt(0)
	v_cvt_pk_bf16_f32 v211, v144, v145
	ds_read2_b32 v[138:139], v162 offset0:40 offset1:105
	ds_read2_b32 v[140:141], v162 offset0:170 offset1:235
	ds_read2_b32 v[142:143], v177 offset0:44 offset1:109
	ds_read2_b32 v[144:145], v177 offset0:174 offset1:239
	v_lshlrev_b32_e32 v134, 6, v134
	v_add_lshl_u32 v134, v134, s2, 1
	v_lshl_add_u64 v[212:213], s[30:31], 0, v[134:135]
	v_mov_b32_e32 v137, v135
	v_lshl_add_u64 v[212:213], v[212:213], 0, v[136:137]
	s_and_b64 vcc, exec, s[6:7]
	global_store_dwordx4 v[212:213], v[208:211], off nt
	s_cbranch_vccnz .LBB0_223
	s_lshr_b32 s2, s52, 1
	v_or_b32_e32 v134, s2, v160
	s_movk_i32 s2, 0x2000
	s_cbranch_execnz .LBB0_202

.LBB0_202:
	s_waitcnt lgkmcnt(3)
	v_cvt_pk_bf16_f32 v208, v138, v139
	s_waitcnt lgkmcnt(2)
	v_cvt_pk_bf16_f32 v209, v140, v141
	s_waitcnt lgkmcnt(1)
	v_cvt_pk_bf16_f32 v210, v142, v143
	s_waitcnt lgkmcnt(0)
	v_cvt_pk_bf16_f32 v211, v144, v145
	ds_read2_b32 v[138:139], v162 offset0:48 offset1:113
	ds_read2_b32 v[140:141], v162 offset0:178 offset1:243
	ds_read2_b32 v[142:143], v177 offset0:52 offset1:117
	ds_read2_b32 v[144:145], v177 offset0:182 offset1:247
	v_add_u32_e32 v134, v134, v167
	v_lshl_or_b32 v134, v134, 6, v171
	v_add_lshl_u32 v134, v134, s2, 1
	v_lshl_add_u64 v[212:213], s[30:31], 0, v[134:135]
	v_mov_b32_e32 v137, v135
	v_lshl_add_u64 v[212:213], v[212:213], 0, v[136:137]
	s_and_b64 vcc, exec, s[6:7]
	global_store_dwordx4 v[212:213], v[208:211], off nt
	s_cbranch_vccnz .LBB0_224
	s_lshr_b32 s2, s52, 1
	v_or_b32_e32 v134, s2, v168
	s_movk_i32 s2, 0x2000
	s_cbranch_execnz .LBB0_205

.LBB0_205:
	s_waitcnt lgkmcnt(3)
	v_cvt_pk_bf16_f32 v208, v138, v139
	s_waitcnt lgkmcnt(2)
	v_cvt_pk_bf16_f32 v209, v140, v141
	s_waitcnt lgkmcnt(1)
	v_cvt_pk_bf16_f32 v210, v142, v143
	s_waitcnt lgkmcnt(0)
	v_cvt_pk_bf16_f32 v211, v144, v145
	ds_read2_b32 v[138:139], v162 offset0:56 offset1:121
	ds_read2_b32 v[140:141], v162 offset0:186 offset1:251
	ds_read2_b32 v[142:143], v177 offset0:60 offset1:125
	ds_read2_b32 v[144:145], v177 offset0:190 offset1:255
	v_lshl_or_b32 v134, v134, 6, v172
	v_add_lshl_u32 v134, v134, s2, 1
	v_lshl_add_u64 v[212:213], s[30:31], 0, v[134:135]
	v_mov_b32_e32 v137, v135
	v_lshl_add_u64 v[212:213], v[212:213], 0, v[136:137]
	s_and_b64 vcc, exec, s[6:7]
	global_store_dwordx4 v[212:213], v[208:211], off nt
	s_cbranch_vccnz .LBB0_225
	s_lshr_b32 s2, s52, 1
	v_or_b32_e32 v134, s2, v160
	s_movk_i32 s2, 0x2000
	s_cbranch_execnz .LBB0_208

.LBB0_208:
	v_or_b32_e32 v134, v134, v161
	v_lshl_or_b32 v134, v134, 6, v173
	v_add_lshl_u32 v134, v134, s2, 1
	s_waitcnt lgkmcnt(3)
	v_cvt_pk_bf16_f32 v138, v138, v139
	s_waitcnt lgkmcnt(2)
	v_cvt_pk_bf16_f32 v139, v140, v141
	s_waitcnt lgkmcnt(1)
	v_cvt_pk_bf16_f32 v140, v142, v143
	v_lshl_add_u64 v[142:143], s[30:31], 0, v[134:135]
	v_mov_b32_e32 v137, v135
	s_waitcnt lgkmcnt(0)
	v_cvt_pk_bf16_f32 v141, v144, v145
	v_lshl_add_u64 v[142:143], v[142:143], 0, v[136:137]
	global_store_dwordx4 v[142:143], v[138:141], off nt
	s_waitcnt lgkmcnt(0)
	s_andn2_b64 vcc, exec, s[36:37]
	s_cbranch_vccnz .LBB0_156
	s_add_i32 s36, s54, s42
	s_add_i32 s37, s49, s53
	s_cmp_gt_i32 s37, 0xb3ff
	s_cbranch_scc1 .LBB0_242
	s_cmpk_gt_i32 s37, 0xfff
	s_mov_b64 s[4:5], -1
	s_cbranch_scc0 .LBB0_239
	s_cmpk_gt_u32 s37, 0x1bff
	s_cbranch_scc0 .LBB0_226
	s_cmpk_gt_u32 s37, 0x1fff
	s_cbranch_scc0 .LBB0_227
	s_cmpk_gt_u32 s37, 0x2fff
	s_cbranch_scc0 .LBB0_228
	s_cmpk_gt_u32 s37, 0x33ff
	s_cbranch_scc0 .LBB0_230
	s_cmpk_gt_u32 s37, 0x73ff
	s_cbranch_scc0 .LBB0_217
	s_add_i32 s4, s37, 0xffff8c00
	s_lshr_b32 s2, s4, 12
	s_and_b32 s41, s4, 0xfff
	s_lshl_b64 s[4:5], s[2:3], 26
	s_add_u32 s30, s18, s4
	s_addc_u32 s31, s19, s5
	s_lshl_b64 s[4:5], s[2:3], 25
	s_add_u32 s6, s43, s4
	s_addc_u32 s7, s44, s5
	s_mov_b64 s[4:5], 0

.LBB0_247:
	v_lshlrev_b32_e32 v134, 6, v134
	v_add_lshl_u32 v134, v134, s2, 1
	s_waitcnt lgkmcnt(3)
	v_cvt_pk_bf16_f32 v180, v138, v139
	v_lshl_add_u64 v[138:139], s[34:35], 0, v[134:135]
	v_mov_b32_e32 v137, v135
	s_waitcnt lgkmcnt(2)
	v_cvt_pk_bf16_f32 v181, v140, v141
	s_waitcnt lgkmcnt(1)
	v_cvt_pk_bf16_f32 v182, v142, v143
	s_waitcnt lgkmcnt(0)
	v_cvt_pk_bf16_f32 v183, v144, v145
	v_lshl_add_u64 v[184:185], v[138:139], 0, v[136:137]
	ds_read2_b32 v[138:139], v162 offset0:8 offset1:73
	ds_read2_b32 v[140:141], v162 offset0:138 offset1:203
	ds_read2_b32 v[142:143], v177 offset0:12 offset1:77
	ds_read2_b32 v[144:145], v177 offset0:142 offset1:207
	v_cndmask_b32_e64 v134, 0, 1, s[8:9]
	v_cmp_ne_u32_e64 s[6:7], 1, v134
	s_andn2_b64 vcc, exec, s[8:9]
	global_store_dwordx4 v[184:185], v[180:183], off nt
	s_cbranch_vccnz .LBB0_269
	s_lshr_b32 s2, s40, 1
	v_or_b32_e32 v134, s2, v160
	s_mov_b32 s2, 0
	v_bitop3_b32 v179, s40, v170, v160 bitop3:0xc8
	s_cbranch_execnz .LBB0_250

.LBB0_250:
	s_waitcnt lgkmcnt(3)
	v_cvt_pk_bf16_f32 v180, v138, v139
	s_waitcnt lgkmcnt(2)
	v_cvt_pk_bf16_f32 v181, v140, v141
	s_waitcnt lgkmcnt(1)
	v_cvt_pk_bf16_f32 v182, v142, v143
	s_waitcnt lgkmcnt(0)
	v_cvt_pk_bf16_f32 v183, v144, v145
	ds_read2_b32 v[138:139], v162 offset0:16 offset1:81
	ds_read2_b32 v[140:141], v162 offset0:146 offset1:211
	ds_read2_b32 v[142:143], v177 offset0:20 offset1:85
	ds_read2_b32 v[144:145], v177 offset0:150 offset1:215
	v_add_u32_e32 v134, v134, v167
	v_lshl_or_b32 v134, v134, 6, v171
	v_add_lshl_u32 v134, v134, s2, 1
	v_lshl_add_u64 v[184:185], s[34:35], 0, v[134:135]
	v_mov_b32_e32 v137, v135
	v_lshl_add_u64 v[184:185], v[184:185], 0, v[136:137]
	s_and_b64 vcc, exec, s[6:7]
	global_store_dwordx4 v[184:185], v[180:183], off nt
	s_cbranch_vccnz .LBB0_270
	s_lshr_b32 s2, s40, 1
	v_or_b32_e32 v134, s2, v168
	s_mov_b32 s2, 0
	s_cbranch_execnz .LBB0_253

.LBB0_253:
	s_waitcnt lgkmcnt(3)
	v_cvt_pk_bf16_f32 v180, v138, v139
	s_waitcnt lgkmcnt(2)
	v_cvt_pk_bf16_f32 v181, v140, v141
	s_waitcnt lgkmcnt(1)
	v_cvt_pk_bf16_f32 v182, v142, v143
	s_waitcnt lgkmcnt(0)
	v_cvt_pk_bf16_f32 v183, v144, v145
	ds_read2_b32 v[138:139], v162 offset0:24 offset1:89
	ds_read2_b32 v[140:141], v162 offset0:154 offset1:219
	ds_read2_b32 v[142:143], v177 offset0:28 offset1:93
	ds_read2_b32 v[144:145], v177 offset0:158 offset1:223
	v_lshl_or_b32 v134, v134, 6, v172
	v_add_lshl_u32 v134, v134, s2, 1
	v_lshl_add_u64 v[184:185], s[34:35], 0, v[134:135]
	v_mov_b32_e32 v137, v135
	v_lshl_add_u64 v[184:185], v[184:185], 0, v[136:137]
	s_and_b64 vcc, exec, s[6:7]
	global_store_dwordx4 v[184:185], v[180:183], off nt
	s_cbranch_vccnz .LBB0_271
	s_lshr_b32 s2, s40, 1
	v_or_b32_e32 v134, s2, v160
	s_mov_b32 s2, 0
	s_cbranch_execnz .LBB0_256

.LBB0_256:
	s_waitcnt lgkmcnt(3)
	v_cvt_pk_bf16_f32 v178, v138, v139
	s_waitcnt lgkmcnt(2)
	v_cvt_pk_bf16_f32 v179, v140, v141
	s_waitcnt lgkmcnt(1)
	v_cvt_pk_bf16_f32 v180, v142, v143
	s_waitcnt lgkmcnt(0)
	v_cvt_pk_bf16_f32 v181, v144, v145
	ds_read2_b32 v[138:139], v162 offset0:32 offset1:97
	ds_read2_b32 v[140:141], v162 offset0:162 offset1:227
	ds_read2_b32 v[142:143], v177 offset0:36 offset1:101
	ds_read2_b32 v[144:145], v177 offset0:166 offset1:231
	v_or_b32_e32 v134, v134, v161
	v_lshl_or_b32 v134, v134, 6, v173
	v_add_lshl_u32 v134, v134, s2, 1
	v_lshl_add_u64 v[182:183], s[34:35], 0, v[134:135]
	v_mov_b32_e32 v137, v135
	v_lshl_add_u64 v[182:183], v[182:183], 0, v[136:137]
	s_and_b64 vcc, exec, s[6:7]
	global_store_dwordx4 v[182:183], v[178:181], off nt
	s_cbranch_vccnz .LBB0_272
	s_lshr_b32 s2, s40, 1
	v_or_b32_e32 v134, s2, v168
	s_movk_i32 s2, 0x2000
	s_cbranch_execnz .LBB0_259

.LBB0_259:
	s_waitcnt lgkmcnt(3)
	v_cvt_pk_bf16_f32 v178, v138, v139
	s_waitcnt lgkmcnt(2)
	v_cvt_pk_bf16_f32 v179, v140, v141
	s_waitcnt lgkmcnt(1)
	v_cvt_pk_bf16_f32 v180, v142, v143
	s_waitcnt lgkmcnt(0)
	v_cvt_pk_bf16_f32 v181, v144, v145
	ds_read2_b32 v[138:139], v162 offset0:40 offset1:105
	ds_read2_b32 v[140:141], v162 offset0:170 offset1:235
	ds_read2_b32 v[142:143], v177 offset0:44 offset1:109
	ds_read2_b32 v[144:145], v177 offset0:174 offset1:239
	v_lshlrev_b32_e32 v134, 6, v134
	v_add_lshl_u32 v134, v134, s2, 1
	v_lshl_add_u64 v[182:183], s[34:35], 0, v[134:135]
	v_mov_b32_e32 v137, v135
	v_lshl_add_u64 v[182:183], v[182:183], 0, v[136:137]
	s_and_b64 vcc, exec, s[6:7]
	global_store_dwordx4 v[182:183], v[178:181], off nt
	s_cbranch_vccnz .LBB0_273
	s_lshr_b32 s2, s40, 1
	v_or_b32_e32 v134, s2, v160
	s_movk_i32 s2, 0x2000
	s_cbranch_execnz .LBB0_262

.LBB0_262:
	s_waitcnt lgkmcnt(3)
	v_cvt_pk_bf16_f32 v178, v138, v139
	s_waitcnt lgkmcnt(2)
	v_cvt_pk_bf16_f32 v179, v140, v141
	s_waitcnt lgkmcnt(1)
	v_cvt_pk_bf16_f32 v180, v142, v143
	s_waitcnt lgkmcnt(0)
	v_cvt_pk_bf16_f32 v181, v144, v145
	ds_read2_b32 v[138:139], v162 offset0:48 offset1:113
	ds_read2_b32 v[140:141], v162 offset0:178 offset1:243
	ds_read2_b32 v[142:143], v177 offset0:52 offset1:117
	ds_read2_b32 v[144:145], v177 offset0:182 offset1:247
	v_add_u32_e32 v134, v134, v167
	v_lshl_or_b32 v134, v134, 6, v171
	v_add_lshl_u32 v134, v134, s2, 1
	v_lshl_add_u64 v[182:183], s[34:35], 0, v[134:135]
	v_mov_b32_e32 v137, v135
	v_lshl_add_u64 v[182:183], v[182:183], 0, v[136:137]
	s_and_b64 vcc, exec, s[6:7]
	global_store_dwordx4 v[182:183], v[178:181], off nt
	s_cbranch_vccnz .LBB0_274
	s_lshr_b32 s2, s40, 1
	v_or_b32_e32 v134, s2, v168
	s_movk_i32 s2, 0x2000
	s_cbranch_execnz .LBB0_265

.LBB0_265:
	s_waitcnt lgkmcnt(3)
	v_cvt_pk_bf16_f32 v178, v138, v139
	s_waitcnt lgkmcnt(2)
	v_cvt_pk_bf16_f32 v179, v140, v141
	s_waitcnt lgkmcnt(1)
	v_cvt_pk_bf16_f32 v180, v142, v143
	s_waitcnt lgkmcnt(0)
	v_cvt_pk_bf16_f32 v181, v144, v145
	ds_read2_b32 v[138:139], v162 offset0:56 offset1:121
	ds_read2_b32 v[140:141], v162 offset0:186 offset1:251
	ds_read2_b32 v[142:143], v177 offset0:60 offset1:125
	ds_read2_b32 v[144:145], v177 offset0:190 offset1:255
	v_lshl_or_b32 v134, v134, 6, v172
	v_add_lshl_u32 v134, v134, s2, 1
	v_lshl_add_u64 v[182:183], s[34:35], 0, v[134:135]
	v_mov_b32_e32 v137, v135
	v_lshl_add_u64 v[182:183], v[182:183], 0, v[136:137]
	s_and_b64 vcc, exec, s[6:7]
	global_store_dwordx4 v[182:183], v[178:181], off nt
	s_cbranch_vccnz .LBB0_275
	s_lshr_b32 s2, s40, 1
	v_or_b32_e32 v134, s2, v160
	s_movk_i32 s2, 0x2000
	s_cbranch_execnz .LBB0_268

.LBB0_268:
	v_or_b32_e32 v134, v134, v161
	v_lshl_or_b32 v134, v134, 6, v173
	v_add_lshl_u32 v134, v134, s2, 1
	s_waitcnt lgkmcnt(3)
	v_cvt_pk_bf16_f32 v138, v138, v139
	s_waitcnt lgkmcnt(2)
	v_cvt_pk_bf16_f32 v139, v140, v141
	s_waitcnt lgkmcnt(1)
	v_cvt_pk_bf16_f32 v140, v142, v143
	v_lshl_add_u64 v[142:143], s[34:35], 0, v[134:135]
	v_mov_b32_e32 v137, v135
	s_waitcnt lgkmcnt(0)
	v_cvt_pk_bf16_f32 v141, v144, v145
	v_lshl_add_u64 v[142:143], v[142:143], 0, v[136:137]
	global_store_dwordx4 v[142:143], v[138:141], off nt
	s_waitcnt lgkmcnt(0)
	s_cmp_gt_i32 s36, 0xb3ff
	s_cselect_b64 s[4:5], -1, 0
	s_and_b64 vcc, exec, s[4:5]
	s_mov_b32 s53, s36
	s_cbranch_vccz .LBB0_157
	s_branch .LBB0_277
